# MLA loop: VALU chunks between MFMAs re-spaced with a 5/3 cost weight for transcendentals instead of 2
# baseline (speedup 1.0000x reference)
; DI unsigned pk2(float a, float b) { f32x2 v = {a, b}; return __builtin_bit_cast(unsigned, __builtin_convertvector(v, bf2_t)); }
; #define MFMA32(a, b, c) __builtin_amdgcn_mfma_f32_32x32x16_bf16((a), (b), (c), 0, 0, 0)
;     ...
;                 float mx = fmaxf(s4[0][0].x, s4[1][0].x);
; #pragma unroll
;                 for (int qd = 0; qd < 4; ++qd) {
;                     mx = fmaxf(fmaxf(mx, s4[0][qd].y), s4[1][qd].y);
;                     mx = fmaxf(fmaxf(mx, s4[0][qd].z), s4[1][qd].z);
;                     mx = fmaxf(fmaxf(mx, s4[0][qd].w), s4[1][qd].w);
;                     if (qd < 3) mx = fmaxf(fmaxf(mx, s4[0][qd + 1].x), s4[1][qd + 1].x);
;                 }
;                 mx = xhalf_max(mx);
;                 const float mn = fmaxf(m, mx), alpha = fexp2(m - mn);
;                 m = mn;
;                 f32x4 ps4 = {0.f, 0.f, 0.f, 0.f};
;                 const float nmn = -mn;
;                 const f32x4 nm4 = {nmn, nmn, nmn, nmn};
;                 if (__builtin_amdgcn_ballot_w64(alpha != 1.f) != 0) { o0 *= alpha; o1 *= alpha; }
; #pragma unroll
;                 for (int s2 = 0; s2 < 4; ++s2) {
;                     const int mt = s2 >> 1, s = s2 & 1;
;                     f32x4 da = s4[mt][2 * s] + nm4, db = s4[mt][2 * s + 1] + nm4;
;                     da.x = fexp2(da.x); da.y = fexp2(da.y); da.z = fexp2(da.z); da.w = fexp2(da.w);
;                     db.x = fexp2(db.x); db.y = fexp2(db.y); db.z = fexp2(db.z); db.w = fexp2(db.w);
;                     ps4 += da; ps4 += db;
;                     u32x4 pp;
;                     pp.x = pk2(da.x, da.y); pp.y = pk2(da.z, da.w); pp.z = pk2(db.x, db.y); pp.w = pk2(db.z, db.w);
;                     const bf16x8 pfr = __builtin_bit_cast(bf16x8, pp);
;                     const s16x4 a0 = *(const s16x4*)(sV + r * LS + 16 * s2 + 4 * h), a1 = *(const s16x4*)(sV + r * LS + 16 * s2 + 8 + 4 * h);
;                     const s16x4 b0 = *(const s16x4*)(sV + (32 + r) * LS + 16 * s2 + 4 * h), b1 = *(const s16x4*)(sV + (32 + r) * LS + 16 * s2 + 8 + 4 * h);
;                     const bf16x8 v0 = __builtin_shufflevector(a0, a1, 0, 1, 2, 3, 4, 5, 6, 7), v1 = __builtin_shufflevector(b0, b1, 0, 1, 2, 3, 4, 5, 6, 7);
;                     o0 = MFMA32(v0, pfr, o0);
;                     o1 = MFMA32(v1, pfr, o1);
;                 }
;                 lsum = lsum * alpha + ((ps4.x + ps4.y) + (ps4.z + ps4.w));
.Lm3_back_e:
	s_waitcnt lgkmcnt(4)
	v_mfma_f32_32x32x16_bf16 v[176:191], v[208:211], v[86:89], v[156:171]
	v_exp_f32_e32 v50, v50
	v_exp_f32_e32 v51, v51
	v_exp_f32_e32 v52, v52
	v_mfma_f32_32x32x16_bf16 v[192:207], v[232:235], v[86:89], v[156:171]
	ds_read_b128 v[208:211], v216 offset:22880
	ds_read_b128 v[232:235], v216 offset:29536
	v_exp_f32_e32 v53, v53
	v_exp_f32_e32 v54, v54
	v_exp_f32_e32 v55, v55
	s_waitcnt lgkmcnt(4)
	v_mfma_f32_32x32x16_bf16 v[176:191], v[236:239], v[90:93], v[176:191]
	v_exp_f32_e32 v56, v56
	v_exp_f32_e32 v57, v57
	v_cvt_pk_bf16_f32 v142, v50, v51
	v_cvt_pk_bf16_f32 v143, v52, v53
	v_mfma_f32_32x32x16_bf16 v[192:207], v[240:243], v[90:93], v[192:207]
	ds_read_b128 v[236:239], v231 offset:13312
	ds_read_b128 v[240:243], v231 offset:17920
	v_cvt_pk_bf16_f32 v144, v54, v55
	v_cvt_pk_bf16_f32 v145, v56, v57
	v_exp_f32_e32 v58, v58
	v_exp_f32_e32 v59, v59
	s_waitcnt lgkmcnt(4)
	v_mfma_f32_32x32x16_bf16 v[176:191], v[244:247], v[94:97], v[176:191]
	v_exp_f32_e32 v60, v60
	v_exp_f32_e32 v61, v61
	v_exp_f32_e32 v62, v62
	v_mfma_f32_32x32x16_bf16 v[192:207], v[248:251], v[94:97], v[192:207]
	ds_read_b128 v[244:247], v216 offset:22912
	ds_read_b128 v[248:251], v216 offset:29568
	v_exp_f32_e32 v63, v63
	v_exp_f32_e32 v64, v64
	v_exp_f32_e32 v65, v65
	s_waitcnt lgkmcnt(4)
	v_mfma_f32_32x32x16_bf16 v[176:191], v[208:211], v[98:101], v[176:191]
	v_cvt_pk_bf16_f32 v146, v58, v59
	v_cvt_pk_bf16_f32 v147, v60, v61
	v_cvt_pk_bf16_f32 v148, v62, v63
	v_cvt_pk_bf16_f32 v149, v64, v65
	v_mfma_f32_32x32x16_bf16 v[192:207], v[232:235], v[98:101], v[192:207]
	ds_read_b128 v[208:211], v231 offset:13344
	ds_read_b128 v[232:235], v231 offset:17952
	v_exp_f32_e32 v34, v34
	v_exp_f32_e32 v35, v35
	v_exp_f32_e32 v36, v36
	v_exp_f32_e32 v37, v37
	s_waitcnt lgkmcnt(4)
	v_mfma_f32_32x32x16_bf16 v[18:33], v[236:239], v[142:145], v[18:33]
	v_exp_f32_e32 v38, v38
	v_exp_f32_e32 v39, v39
	v_exp_f32_e32 v40, v40
	v_mfma_f32_32x32x16_bf16 v[2:17], v[240:243], v[142:145], v[2:17]
	ds_read_b128 v[236:239], v216 offset:22944
	ds_read_b128 v[240:243], v216 offset:29600
	v_exp_f32_e32 v41, v41
	v_cvt_pk_bf16_f32 v150, v34, v35
	v_cvt_pk_bf16_f32 v151, v36, v37
	v_cvt_pk_bf16_f32 v152, v38, v39
	s_waitcnt lgkmcnt(4)
	v_mfma_f32_32x32x16_bf16 v[176:191], v[244:247], v[102:105], v[176:191]
	v_cvt_pk_bf16_f32 v153, v40, v41
	v_exp_f32_e32 v42, v42
	v_exp_f32_e32 v43, v43
	v_mfma_f32_32x32x16_bf16 v[192:207], v[248:251], v[102:105], v[192:207]
	s_waitcnt vmcnt(0)
	ds_write2_b64 v138, v[78:79], v[80:81] offset1:2
	ds_read_b128 v[244:247], v231 offset:13376
	ds_read_b128 v[248:251], v231 offset:17984
	v_exp_f32_e32 v44, v44
	v_exp_f32_e32 v45, v45
	v_exp_f32_e32 v46, v46
	s_waitcnt lgkmcnt(5)
	v_mfma_f32_32x32x16_bf16 v[18:33], v[208:211], v[146:149], v[18:33]
	ds_write2_b64 v139, v[82:83], v[84:85] offset1:2
	v_exp_f32_e32 v47, v47
	v_exp_f32_e32 v48, v48
	v_exp_f32_e32 v49, v49
	v_cvt_pk_bf16_f32 v142, v42, v43
	v_mfma_f32_32x32x16_bf16 v[2:17], v[232:235], v[146:149], v[2:17]
	ds_read_b128 v[208:211], v231 offset:13408
	ds_read_b128 v[232:235], v231 offset:18016
	v_cvt_pk_bf16_f32 v143, v44, v45
	v_cvt_pk_bf16_f32 v144, v46, v47
	v_cvt_pk_bf16_f32 v145, v48, v49
	v_add_f32_e32 v141, v50, v51
	v_add_f32_e32 v154, v52, v53
	s_waitcnt lgkmcnt(6)
	v_mfma_f32_32x32x16_bf16 v[176:191], v[236:239], v[106:109], v[176:191]
	s_mov_b64 exec, s[24:25]
	ds_write_b128 v127, v[66:69]
	ds_write_b128 v128, v[70:73]
	ds_write_b128 v129, v[74:77]
	s_mov_b64 exec, -1
	v_add_f32_e32 v212, v54, v55
	v_add_f32_e32 v213, v56, v57
	v_add_f32_e32 v141, v141, v154
	v_add_f32_e32 v212, v212, v213
	v_add_f32_e32 v230, v141, v212
	v_mfma_f32_32x32x16_bf16 v[192:207], v[240:243], v[106:109], v[192:207]
	v_add_f32_e32 v141, v58, v59
	v_add_f32_e32 v154, v60, v61
	v_add_f32_e32 v212, v62, v63
	v_add_f32_e32 v213, v64, v65
	v_add_f32_e32 v141, v141, v154
	s_waitcnt lgkmcnt(6)
	v_mfma_f32_32x32x16_bf16 v[18:33], v[244:247], v[150:153], v[18:33]
	v_add_f32_e32 v212, v212, v213
	v_add_f32_e32 v141, v141, v212
	v_add_f32_e32 v230, v230, v141
	v_add_f32_e32 v141, v34, v35
	v_add_f32_e32 v154, v36, v37
	v_mfma_f32_32x32x16_bf16 v[2:17], v[248:251], v[150:153], v[2:17]
	v_add_f32_e32 v212, v38, v39
	v_add_f32_e32 v213, v40, v41
	v_add_f32_e32 v141, v141, v154
	v_add_f32_e32 v212, v212, v213
	v_add_f32_e32 v141, v141, v212
	s_waitcnt lgkmcnt(3)
	v_mfma_f32_32x32x16_bf16 v[18:33], v[208:211], v[142:145], v[18:33]
	v_add_f32_e32 v230, v230, v141
	v_add_f32_e32 v141, v42, v43
	v_add_f32_e32 v154, v44, v45
	v_add_f32_e32 v212, v46, v47
	v_add_f32_e32 v213, v48, v49
	v_mfma_f32_32x32x16_bf16 v[2:17], v[232:235], v[142:145], v[2:17]
	v_add_f32_e32 v141, v141, v154
	v_add_f32_e32 v212, v212, v213
	v_add_f32_e32 v141, v141, v212
	v_add_f32_e32 v230, v230, v141
	v_add_f32_e32 v135, v135, v230
	s_add_i32 s12, s12, 1
	s_add_i32 s16, s16, 64
	s_add_i32 s17, s12, 1
	s_cmp_ge_u32 s17, s66
	s_cbranch_scc1 .Lm3_final
	s_add_i32 s48, s16, 64
	s_lshl_b64 s[14:15], s[48:49], 1
	s_add_u32 s14, s6, s14
	s_addc_u32 s15, s7, s15
	global_load_dwordx4 v[78:81], v116, s[14:15]
	global_load_dwordx4 v[82:85], v118, s[14:15]
	s_add_i32 s48, s16, 0x80
	s_mul_i32 s14, s48, 0xc0
	s_mul_hi_u32 s13, s48, 0xc0
	s_add_u32 s14, s4, s14
	s_addc_u32 s15, s5, s13
	global_load_dwordx4 v[66:69], v0, s[14:15]
	global_load_dwordx4 v[70:73], v112, s[14:15]
	global_load_dwordx4 v[74:77], v114, s[14:15]
	s_waitcnt lgkmcnt(0)
	s_mov_b64 s[26:27], exec
	s_mov_b64 exec, 1
	ds_add_u32 v155, v172
	s_mov_b64 exec, s[26:27]
	s_add_u32 s30, s30, 4

; DI unsigned pk2(float a, float b) { f32x2 v = {a, b}; return __builtin_bit_cast(unsigned, __builtin_convertvector(v, bf2_t)); }
; #define MFMA32(a, b, c) __builtin_amdgcn_mfma_f32_32x32x16_bf16((a), (b), (c), 0, 0, 0)
;     ...
;                 float mx = fmaxf(s4[0][0].x, s4[1][0].x);
; #pragma unroll
;                 for (int qd = 0; qd < 4; ++qd) {
;                     mx = fmaxf(fmaxf(mx, s4[0][qd].y), s4[1][qd].y);
;                     mx = fmaxf(fmaxf(mx, s4[0][qd].z), s4[1][qd].z);
;                     mx = fmaxf(fmaxf(mx, s4[0][qd].w), s4[1][qd].w);
;                     if (qd < 3) mx = fmaxf(fmaxf(mx, s4[0][qd + 1].x), s4[1][qd + 1].x);
;                 }
;                 mx = xhalf_max(mx);
;                 const float mn = fmaxf(m, mx), alpha = fexp2(m - mn);
;                 m = mn;
;                 f32x4 ps4 = {0.f, 0.f, 0.f, 0.f};
;                 const float nmn = -mn;
;                 const f32x4 nm4 = {nmn, nmn, nmn, nmn};
;                 if (__builtin_amdgcn_ballot_w64(alpha != 1.f) != 0) { o0 *= alpha; o1 *= alpha; }
; #pragma unroll
;                 for (int s2 = 0; s2 < 4; ++s2) {
;                     const int mt = s2 >> 1, s = s2 & 1;
;                     f32x4 da = s4[mt][2 * s] + nm4, db = s4[mt][2 * s + 1] + nm4;
;                     da.x = fexp2(da.x); da.y = fexp2(da.y); da.z = fexp2(da.z); da.w = fexp2(da.w);
;                     db.x = fexp2(db.x); db.y = fexp2(db.y); db.z = fexp2(db.z); db.w = fexp2(db.w);
;                     ps4 += da; ps4 += db;
;                     u32x4 pp;
;                     pp.x = pk2(da.x, da.y); pp.y = pk2(da.z, da.w); pp.z = pk2(db.x, db.y); pp.w = pk2(db.z, db.w);
;                     const bf16x8 pfr = __builtin_bit_cast(bf16x8, pp);
;                     const s16x4 a0 = *(const s16x4*)(sV + r * LS + 16 * s2 + 4 * h), a1 = *(const s16x4*)(sV + r * LS + 16 * s2 + 8 + 4 * h);
;                     const s16x4 b0 = *(const s16x4*)(sV + (32 + r) * LS + 16 * s2 + 4 * h), b1 = *(const s16x4*)(sV + (32 + r) * LS + 16 * s2 + 8 + 4 * h);
;                     const bf16x8 v0 = __builtin_shufflevector(a0, a1, 0, 1, 2, 3, 4, 5, 6, 7), v1 = __builtin_shufflevector(b0, b1, 0, 1, 2, 3, 4, 5, 6, 7);
;                     o0 = MFMA32(v0, pfr, o0);
;                     o1 = MFMA32(v1, pfr, o1);
;                 }
;                 lsum = lsum * alpha + ((ps4.x + ps4.y) + (ps4.z + ps4.w));
.Lm3_back_o:
	s_waitcnt lgkmcnt(4)
	v_mfma_f32_32x32x16_bf16 v[50:65], v[208:211], v[86:89], v[156:171]
	v_exp_f32_e32 v176, v176
	v_exp_f32_e32 v177, v177
	v_exp_f32_e32 v178, v178
	v_mfma_f32_32x32x16_bf16 v[34:49], v[232:235], v[86:89], v[156:171]
	ds_read_b128 v[208:211], v216 offset:96
	ds_read_b128 v[232:235], v216 offset:6752
	v_exp_f32_e32 v179, v179
	v_exp_f32_e32 v180, v180
	v_exp_f32_e32 v181, v181
	s_waitcnt lgkmcnt(4)
	v_mfma_f32_32x32x16_bf16 v[50:65], v[236:239], v[90:93], v[50:65]
	v_exp_f32_e32 v182, v182
	v_exp_f32_e32 v183, v183
	v_cvt_pk_bf16_f32 v142, v176, v177
	v_cvt_pk_bf16_f32 v143, v178, v179
	v_mfma_f32_32x32x16_bf16 v[34:49], v[240:243], v[90:93], v[34:49]
	ds_read_b128 v[236:239], v231 offset:36096
	ds_read_b128 v[240:243], v231 offset:40704
	v_cvt_pk_bf16_f32 v144, v180, v181
	v_cvt_pk_bf16_f32 v145, v182, v183
	v_exp_f32_e32 v184, v184
	v_exp_f32_e32 v185, v185
	s_waitcnt lgkmcnt(4)
	v_mfma_f32_32x32x16_bf16 v[50:65], v[244:247], v[94:97], v[50:65]
	v_exp_f32_e32 v186, v186
	v_exp_f32_e32 v187, v187
	v_exp_f32_e32 v188, v188
	v_mfma_f32_32x32x16_bf16 v[34:49], v[248:251], v[94:97], v[34:49]
	ds_read_b128 v[244:247], v216 offset:128
	ds_read_b128 v[248:251], v216 offset:6784
	v_exp_f32_e32 v189, v189
	v_exp_f32_e32 v190, v190
	v_exp_f32_e32 v191, v191
	s_waitcnt lgkmcnt(4)
	v_mfma_f32_32x32x16_bf16 v[50:65], v[208:211], v[98:101], v[50:65]
	v_cvt_pk_bf16_f32 v146, v184, v185
	v_cvt_pk_bf16_f32 v147, v186, v187
	v_cvt_pk_bf16_f32 v148, v188, v189
	v_cvt_pk_bf16_f32 v149, v190, v191
	v_mfma_f32_32x32x16_bf16 v[34:49], v[232:235], v[98:101], v[34:49]
	ds_read_b128 v[208:211], v231 offset:36128
	ds_read_b128 v[232:235], v231 offset:40736
	v_exp_f32_e32 v192, v192
	v_exp_f32_e32 v193, v193
	v_exp_f32_e32 v194, v194
	v_exp_f32_e32 v195, v195
	s_waitcnt lgkmcnt(4)
	v_mfma_f32_32x32x16_bf16 v[18:33], v[236:239], v[142:145], v[18:33]
	v_exp_f32_e32 v196, v196
	v_exp_f32_e32 v197, v197
	v_exp_f32_e32 v198, v198
	v_mfma_f32_32x32x16_bf16 v[2:17], v[240:243], v[142:145], v[2:17]
	ds_read_b128 v[236:239], v216 offset:160
	ds_read_b128 v[240:243], v216 offset:6816
	v_exp_f32_e32 v199, v199
	v_cvt_pk_bf16_f32 v150, v192, v193
	v_cvt_pk_bf16_f32 v151, v194, v195
	v_cvt_pk_bf16_f32 v152, v196, v197
	s_waitcnt lgkmcnt(4)
	v_mfma_f32_32x32x16_bf16 v[50:65], v[244:247], v[102:105], v[50:65]
	v_cvt_pk_bf16_f32 v153, v198, v199
	v_exp_f32_e32 v200, v200
	v_exp_f32_e32 v201, v201
	v_mfma_f32_32x32x16_bf16 v[34:49], v[248:251], v[102:105], v[34:49]
	s_waitcnt vmcnt(0)
	ds_write2_b64 v130, v[78:79], v[80:81] offset1:2
	ds_read_b128 v[244:247], v231 offset:36160
	ds_read_b128 v[248:251], v231 offset:40768
	v_exp_f32_e32 v202, v202
	v_exp_f32_e32 v203, v203
	v_exp_f32_e32 v204, v204
	s_waitcnt lgkmcnt(5)
	v_mfma_f32_32x32x16_bf16 v[18:33], v[208:211], v[146:149], v[18:33]
	ds_write2_b64 v132, v[82:83], v[84:85] offset1:2
	v_exp_f32_e32 v205, v205
	v_exp_f32_e32 v206, v206
	v_exp_f32_e32 v207, v207
	v_cvt_pk_bf16_f32 v142, v200, v201
	v_mfma_f32_32x32x16_bf16 v[2:17], v[232:235], v[146:149], v[2:17]
	ds_write_b128 v127, v[66:69] offset:22784
	ds_read_b128 v[208:211], v231 offset:36192
	ds_read_b128 v[232:235], v231 offset:40800
	v_cvt_pk_bf16_f32 v143, v202, v203
	v_cvt_pk_bf16_f32 v144, v204, v205
	v_cvt_pk_bf16_f32 v145, v206, v207
	v_add_f32_e32 v141, v176, v177
	v_add_f32_e32 v154, v178, v179
	s_waitcnt lgkmcnt(7)
	v_mfma_f32_32x32x16_bf16 v[50:65], v[236:239], v[106:109], v[50:65]
	ds_write_b128 v128, v[70:73] offset:22784
	v_add_f32_e32 v212, v180, v181
	v_add_f32_e32 v213, v182, v183
	v_add_f32_e32 v141, v141, v154
	v_add_f32_e32 v212, v212, v213
	v_add_f32_e32 v230, v141, v212
	v_mfma_f32_32x32x16_bf16 v[34:49], v[240:243], v[106:109], v[34:49]
	ds_write_b128 v129, v[74:77] offset:22784
	v_add_f32_e32 v141, v184, v185
	v_add_f32_e32 v154, v186, v187
	v_add_f32_e32 v212, v188, v189
	v_add_f32_e32 v213, v190, v191
	v_add_f32_e32 v141, v141, v154
	s_waitcnt lgkmcnt(6)
	v_mfma_f32_32x32x16_bf16 v[18:33], v[244:247], v[150:153], v[18:33]
	v_add_f32_e32 v212, v212, v213
	v_add_f32_e32 v141, v141, v212
	v_add_f32_e32 v230, v230, v141
	v_add_f32_e32 v141, v192, v193
	v_add_f32_e32 v154, v194, v195
	v_mfma_f32_32x32x16_bf16 v[2:17], v[248:251], v[150:153], v[2:17]
	v_add_f32_e32 v212, v196, v197
	v_add_f32_e32 v213, v198, v199
	v_add_f32_e32 v141, v141, v154
	v_add_f32_e32 v212, v212, v213
	v_add_f32_e32 v141, v141, v212
	s_waitcnt lgkmcnt(2)
	v_mfma_f32_32x32x16_bf16 v[18:33], v[208:211], v[142:145], v[18:33]
	v_add_f32_e32 v230, v230, v141
	v_add_f32_e32 v141, v200, v201
	v_add_f32_e32 v154, v202, v203
	v_add_f32_e32 v212, v204, v205
	v_add_f32_e32 v213, v206, v207
	v_mfma_f32_32x32x16_bf16 v[2:17], v[232:235], v[142:145], v[2:17]
	v_add_f32_e32 v141, v141, v154
	v_add_f32_e32 v212, v212, v213
	v_add_f32_e32 v141, v141, v212
	v_add_f32_e32 v230, v230, v141
	v_add_f32_e32 v135, v135, v230
	s_add_i32 s12, s12, 1
	s_add_i32 s16, s16, 64
	s_branch .Lm3_even
